# thin kv tile: wave ids permuted inside the job so the four MFMA-computing waves sit on four different SIMDs
# speedup vs baseline: 1.0019x; 1.0019x over previous
; __device__ __forceinline__ int get_tid512() { int t = threadIdx.x; asm volatile("" : "+v"(t)); return t; }
; template <bool SWAP, class Epi, bool THIN = false> ...
;   const int tid = get_tid512(), lane = tid & 63, wid = tid >> 6, wr = wid >> 1, wc = wid & 1, fr = lane & 15, fq = lane >> 4;
;   const int NT = (N + 255) >> 8, MT = MTS >> 1, ntiles = MT * NT, ns = K >> 6;
;   const int full = MT >> 3;
;   int v = vid0;
;   if (v < voff) v += ((voff - v + grid - 1) / grid) * grid;
.LBB0_1520:
	v_bfe_u32 v3, v1, 6, 2
	v_lshrrev_b32_e32 v4, 8, v1
	v_lshl_or_b32 v3, v3, 1, v4
	v_and_b32_e32 v2, 63, v1
	v_lshl_or_b32 v2, v3, 6, v2
	s_cmpk_gt_i32 s3, 0x107
	s_cbranch_scc1 .LBB0_1522
	s_abs_i32 s4, s54
	v_cvt_f32_u32_e32 v3, s4
	s_sub_i32 s7, 0, s4
	s_add_i32 s5, s54, 0x107
	s_sub_i32 s3, s5, s3
	v_rcp_iflag_f32_e32 v3, v3
	s_ashr_i32 s6, s3, 31
	s_abs_i32 s3, s3
	v_mul_f32_e32 v3, 0x4f7ffffe, v3
	v_cvt_u32_f32_e32 v3, v3
	s_nop 0
	v_readfirstlane_b32 s8, v3
	s_mul_i32 s7, s7, s8
	s_mul_hi_u32 s7, s8, s7
	s_add_i32 s8, s8, s7
	s_mul_hi_u32 s7, s3, s8
	s_mul_i32 s7, s7, s4
	s_sub_i32 s3, s3, s7
	s_sub_i32 s7, s3, s4
	s_cmp_ge_u32 s3, s4
	s_cselect_b32 s3, s7, s3
	s_sub_i32 s7, s3, s4
	s_cmp_ge_u32 s3, s4
	s_cselect_b32 s3, s7, s3
	s_xor_b32 s3, s3, s6
	s_sub_i32 s3, s6, s3
	s_add_i32 s3, s5, s3

; __device__ __forceinline__ int get_tid512() { int t = threadIdx.x; asm volatile("" : "+v"(t)); return t; }
; __device__ __forceinline__ unsigned pack2(float a, float b) { unsigned r; asm("v_cvt_pk_bf16_f32 %0, %1, %2" : "=v"(r) : "v"(a), "v"(b)); return r; }
;   __device__ __forceinline__ float c4(int g, int rig, int col, f32x4 v) const {
;     const size_t row = (size_t)g * ostride + rig;
;     if (kpe && col >= ropecol) {
;       const int i0 = col - ropecol;
;       f32x4 o = v;
;       const float p0 = __shfl_xor(v[0], 32), p1 = __shfl_xor(v[1], 32), p2 = __shfl_xor(v[2], 32), p3 = __shfl_xor(v[3], 32);
;       const float pv[4] = {p0, p1, p2, p3};
;       if (rig >= 256) {
;         const int t = rig - 256;
;         const int quarter = i0 >> 3;
;         const float pos = (quarter < 2) ? (float)(t >> 6) : (float)(t & 63);
; #pragma unroll
;         for (int j = 0; j < 4; ++j) {
;           const int idx = (i0 & 7) + j;
;           const float inv = exp2f(-(float)idx * (13.287712379549449f / 8.0f));
;           const float ang = pos * inv;
;           const float cs = __cosf(ang), sn = __sinf(ang);
;           o[j] = v[j] * cs + ((quarter & 1) ? pv[j] : -pv[j]) * sn;
;         }
;       }
;       uint2 u; u.x = pack2(o[0], o[1]); u.y = pack2(o[2], o[3]);
;       *(uint2*)(kpe + row * 32 + i0) = u;
; template <bool SWAP, class Epi, bool THIN = false> ...
;     ...
;     const int te = get_tid512();
;     const int fr_e = te & 15, fq_e = (te & 63) >> 4, wr_e = te >> 7, wc_e = (te >> 6) & 1;
;     const int sub = 2 * mt + (wr_e >> 1);
;     const int g = sub / tpg, ti = sub - g * tpg;
;     const int rig0 = ti * step - halo;
;     const int rw = (wr_e & 1) * 64;
;     if constexpr (Epi::KIND == 0) {
; #pragma unroll
;       for (int m = 0; m < 4; ++m) {
;         const int rig = rig0 + rw + m * 16 + fr_e;
;         if constexpr (Epi::ROWSUM) {
;           float ss = 0.f;
; #pragma unroll
;           for (int n = 0; n < 8; ++n) {
;             const int col = nt * 256 + wc_e * 128 + n * 16 + fq_e * 4;
;             if (col < N) ss += epi.c4(g, rig, col, acc[m][n]);
;           }
;           ss += __shfl_xor(ss, 16); ss += __shfl_xor(ss, 32);
;           if (fq_e == 0) epi.rowsum(g, rig, nt * 2 + wc_e, ss);
.LBB0_1557:
	s_or_b64 exec, exec, s[6:7]
	v_bfe_u32 v38, v1, 6, 2
	v_lshrrev_b32_e32 v39, 8, v1
	v_lshl_or_b32 v38, v38, 1, v39
	v_and_b32_e32 v40, 63, v1
	v_lshl_or_b32 v40, v38, 6, v40
	s_waitcnt vmcnt(0) lgkmcnt(0)
	s_barrier
	s_nop 0
	v_ashrrev_i32_e32 v2, 8, v40
	v_add_u32_e32 v2, s9, v2
	v_mul_hi_i32 v38, v2, s33
	v_lshrrev_b32_e32 v39, 31, v38
	v_ashrrev_i32_e32 v38, 2, v38
	v_add_u32_e32 v48, v38, v39
	v_mad_u64_u32 v[38:39], s[6:7], v48, s74, v[2:3]
	v_lshrrev_b32_e32 v2, 1, v40
	v_bfe_u32 v49, v40, 4, 2
	v_bfe_u32 v5, v40, 6, 1
	v_and_b32_e32 v2, 64, v2
	v_and_b32_e32 v4, 15, v40
	v_lshl_or_b32 v42, v38, 7, v2
	v_lshlrev_b32_e32 v2, 7, v5
	v_lshlrev_b32_e32 v50, 2, v49
	v_or3_b32 v2, v2, v50, s8
	v_add_u32_e32 v38, 0xffffff00, v42
	v_or_b32_e32 v44, v42, v4
	v_lshrrev_b32_e32 v51, 6, v38
	v_ashrrev_i32_e32 v45, 31, v44
	v_cmp_lt_i32_e64 s[6:7], s78, v44
	v_cmp_gt_i32_e64 s[8:9], 32, v2
	v_mov_b32_e32 v40, 0
	s_and_saveexec_b64 s[12:13], s[8:9]
	s_cbranch_execz .LBB0_1564
	v_mad_i64_i32 v[46:47], s[10:11], v48, s75, v[44:45]
	s_cmp_lt_i32 s46, 0
	s_cselect_b64 s[10:11], -1, 0
	s_or_b64 s[14:15], s[20:21], s[10:11]
	s_mov_b64 s[10:11], -1
	s_and_b64 vcc, exec, s[14:15]
	s_cbranch_vccnz .LBB0_1562
	v_and_b32_e32 v39, 64, v90
	v_xor_b32_e32 v38, 32, v90
	v_add_u32_e32 v39, 64, v39
	v_cmp_lt_i32_e32 vcc, v38, v39
	s_nop 1
	v_cndmask_b32_e32 v38, v90, v38, vcc
	v_lshlrev_b32_e32 v38, 2, v38
	ds_bpermute_b32 v53, v38, v34
	ds_bpermute_b32 v93, v38, v35
	ds_bpermute_b32 v52, v38, v36
	ds_bpermute_b32 v43, v38, v37
	v_mov_b64_e32 v[40:41], v[36:37]
	v_mov_b64_e32 v[38:39], v[34:35]
	s_and_saveexec_b64 s[14:15], s[6:7]
	s_cbranch_execz .LBB0_1561
	v_and_b32_e32 v96, 4, v50
	v_cvt_f32_ubyte0_e32 v39, v96
	v_cmp_gt_u32_e32 vcc, 16, v2
	v_mul_f32_e32 v40, 0xbfd49a78, v39
	s_nop 0
	v_cndmask_b32_e32 v38, v4, v51, vcc
	v_cmp_gt_f32_e32 vcc, s79, v40
	v_cvt_f32_u32_e32 v97, v38
	s_nop 0
	v_cndmask_b32_e32 v40, 0, v91, vcc
	v_fmac_f32_e32 v40, 0xbfd49a78, v39
	v_exp_f32_e32 v39, v40
	v_cndmask_b32_e32 v38, 0, v92, vcc
	v_ldexp_f32 v38, v39, v38
	v_mul_f32_e32 v38, v38, v97
	v_mul_f32_e32 v39, 0.15915494, v38
	v_or_b32_e32 v38, 1, v96
	v_cvt_f32_ubyte0_e32 v38, v38
	v_mul_f32_e32 v40, 0xbfd49a78, v38
	v_cmp_gt_f32_e32 vcc, s79, v40
	s_nop 1
	v_cndmask_b32_e32 v40, 0, v91, vcc
	v_fmac_f32_e32 v40, 0xbfd49a78, v38
	v_exp_f32_e32 v41, v40
	v_cos_f32_e32 v38, v39
	v_sin_f32_e32 v40, v39
	v_cndmask_b32_e32 v39, 0, v92, vcc
	v_cmp_gt_u32_e32 vcc, 2, v49
	v_ldexp_f32 v39, v41, v39
	v_mul_f32_e32 v39, v39, v97
	s_waitcnt lgkmcnt(2)
	v_cndmask_b32_e64 v95, v93, -v93, vcc
	v_or_b32_e32 v93, 2, v96
	v_cvt_f32_ubyte0_e32 v93, v93
	v_mul_f32_e32 v94, 0xbfd49a78, v93
	v_mul_f32_e32 v41, 0.15915494, v39
	v_cmp_gt_f32_e64 s[10:11], s79, v94
	v_cos_f32_e32 v39, v41
	v_sin_f32_e32 v41, v41
	v_cndmask_b32_e64 v94, 0, v91, s[10:11]
	v_fmac_f32_e32 v94, 0xbfd49a78, v93
	v_exp_f32_e32 v93, v94
	v_cndmask_b32_e64 v94, v53, -v53, vcc
	v_pk_mul_f32 v[40:41], v[40:41], v[94:95]
	v_or_b32_e32 v94, 3, v96
	v_cndmask_b32_e64 v53, 0, v92, s[10:11]
	v_cvt_f32_ubyte0_e32 v94, v94
	v_ldexp_f32 v53, v93, v53
	v_mul_f32_e32 v95, 0xbfd49a78, v94
	v_mul_f32_e32 v53, v53, v97
	v_cmp_gt_f32_e64 s[10:11], s79, v95
	v_mul_f32_e32 v53, 0.15915494, v53
	v_cos_f32_e32 v93, v53
	v_cndmask_b32_e64 v95, 0, v91, s[10:11]
	v_fmac_f32_e32 v95, 0xbfd49a78, v94
	v_exp_f32_e32 v95, v95
	v_mul_f32_e32 v94, v36, v93
	s_waitcnt lgkmcnt(1)
	v_cndmask_b32_e64 v93, v52, -v52, vcc
	v_cndmask_b32_e64 v52, 0, v92, s[10:11]
	v_ldexp_f32 v52, v95, v52
	v_mul_f32_e32 v52, v52, v97
	v_sin_f32_e32 v53, v53
	v_mul_f32_e32 v95, 0.15915494, v52
	v_cos_f32_e32 v52, v95
	v_sin_f32_e32 v97, v95
	v_mul_f32_e32 v98, v53, v93
	s_waitcnt lgkmcnt(0)
	v_cndmask_b32_e64 v53, v43, -v43, vcc
	v_mov_b32_e32 v96, v37
	v_pk_mul_f32 v[52:53], v[96:97], v[52:53]
	v_pk_fma_f32 v[38:39], v[34:35], v[38:39], v[40:41]
	v_mov_b32_e32 v95, v52
	v_mov_b32_e32 v99, v53
	v_pk_add_f32 v[40:41], v[94:95], v[98:99]
